# adaLN RMSNorm phases: all 16 loads of a row (x, gain, scale, shift) issued at the top of the row iteration with counted vmcnt waits
# speedup vs baseline: 1.0685x; 1.0132x over previous
; DI void st4bf(u16* dst, float a, float b, float c, float d) { u32x2 v; v[0] = pack2(a, b); v[1] = pack2(c, d); *(u32x2*)dst = v; }
; DI void phase_norm(const Prm& p, const float* xsrc, const float* g, const float* modl, int shoff, int scoff, int sb) {
;     ...
;   for (int row = gw; row < TB; row += nw) {
;     const int cond = condrow(sb, row);
;     const float* xr = xsrc + (size_t)row * 1024;
;     float4 v[4];
;     float ss = 0.f;
; #pragma unroll
;     for (int i = 0; i < 4; ++i) {
;       v[i] = *(const float4*)(xr + i * 256 + lane * 4);
;       ss += v[i].x * v[i].x + v[i].y * v[i].y + v[i].z * v[i].z + v[i].w * v[i].w;
;     }
; #pragma unroll
;     for (int off = 32; off >= 1; off >>= 1) ss += __shfl_xor(ss, off);
;     const float rstd = rsqrtf(ss * (1.f / 1024.f) + 1e-6f);
;     const float* sc = modl + cond * 6144 + scoff;
;     const float* sh = modl + cond * 6144 + shoff;
; #pragma unroll
;     for (int i = 0; i < 4; ++i) {
;       const int col = i * 256 + lane * 4;
;       const float4 gg = *(const float4*)(g + col), s4 = *(const float4*)(sc + col), h4 = *(const float4*)(sh + col);
;       st4bf(p.hbuf + (size_t)row * 1024 + col,
;             v[i].x * rstd * gg.x * (1.f + s4.x) + h4.x, v[i].y * rstd * gg.y * (1.f + s4.y) + h4.y,
;             v[i].z * rstd * gg.z * (1.f + s4.z) + h4.z, v[i].w * rstd * gg.w * (1.f + s4.w) + h4.w);
;     }
;   }
.LBB0_369:
	v_lshrrev_b32_e32 v3, 11, v2
	v_add_u32_e32 v3, s10, v3
	v_mul_lo_u32 v3, v3, s87
	v_cndmask_b32_e64 v16, v3, 0, s[8:9]
	v_ashrrev_i32_e32 v17, 31, v16
	v_lshl_add_u64 v[16:17], v[16:17], 2, s[12:13]
	s_waitcnt vmcnt(1)
	v_lshl_add_u64 v[44:45], v[16:17], 0, s[6:7]
	v_lshl_add_u64 v[32:33], v[44:45], 0, v[0:1]
	v_lshl_add_u64 v[16:17], v[16:17], 0, v[0:1]
	global_load_dwordx4 v[24:27], v[6:7], off offset:-2048
	global_load_dwordx4 v[28:31], v[4:5], off
	s_nop 0
	global_load_dwordx4 v[32:35], v[32:33], off
	s_nop 0
	global_load_dwordx4 v[36:39], v[16:17], off
	v_lshl_add_u64 v[52:53], v[44:45], 0, v[10:11]
	v_lshl_add_u64 v[56:57], v[44:45], 0, v[12:13]
	v_lshl_add_u64 v[58:59], v[44:45], 0, v[14:15]
	v_add_u32_e32 v2, s84, v2
	global_load_dwordx4 v[72:75], v[6:7], off offset:-1024
	global_load_dwordx4 v[76:79], v[6:7], off offset:1024
	global_load_dwordx4 v[80:83], v[6:7], off
	global_load_dwordx4 v[84:87], v[4:5], off offset:1024
	global_load_dwordx4 v[88:91], v[52:53], off
	global_load_dwordx4 v[92:95], v[16:17], off offset:1024
	global_load_dwordx4 v[96:99], v[4:5], off offset:2048
	global_load_dwordx4 v[100:103], v[56:57], off
	global_load_dwordx4 v[104:107], v[16:17], off offset:2048
	global_load_dwordx4 v[108:111], v[4:5], off offset:3072
	global_load_dwordx4 v[112:115], v[58:59], off
	global_load_dwordx4 v[116:119], v[16:17], off offset:3072
	s_waitcnt vmcnt(15)
	v_mov_b32_e32 v54, v25
	v_mov_b32_e32 v46, v24
	s_waitcnt vmcnt(13)
	v_pk_add_f32 v[48:49], v[34:35], 1.0 op_sel_hi:[1,0]
	v_pk_add_f32 v[50:51], v[32:33], 1.0 op_sel_hi:[1,0]
	v_mov_b32_e32 v40, v26
	v_mov_b32_e32 v42, v27
	s_waitcnt vmcnt(11)
	v_mov_b32_e32 v55, v73
	v_mov_b32_e32 v47, v72
	v_pk_mul_f32 v[54:55], v[54:55], v[54:55]
	v_mov_b32_e32 v41, v74
	v_pk_fma_f32 v[46:47], v[46:47], v[46:47], v[54:55]
	v_mov_b32_e32 v43, v75
	v_pk_fma_f32 v[40:41], v[40:41], v[40:41], v[46:47]
	v_pk_fma_f32 v[54:55], v[42:43], v[42:43], v[40:41]
	v_add_f32_e32 v3, v54, v55
	v_lshl_add_u64 v[6:7], v[6:7], 0, s[4:5]
	s_waitcnt vmcnt(10)
	v_mov_b32_e32 v67, v77
	v_mov_b32_e32 v65, v76
	s_waitcnt vmcnt(9)
	v_mov_b32_e32 v66, v81
	v_mov_b32_e32 v64, v80
	v_pk_mul_f32 v[66:67], v[66:67], v[66:67]
	v_mov_b32_e32 v60, v82
	v_mov_b32_e32 v61, v78
	v_pk_fma_f32 v[64:65], v[64:65], v[64:65], v[66:67]
	v_mov_b32_e32 v62, v83
	v_mov_b32_e32 v63, v79
	v_pk_fma_f32 v[60:61], v[60:61], v[60:61], v[64:65]
	s_nop 0
	v_pk_fma_f32 v[60:61], v[62:63], v[62:63], v[60:61]
	s_nop 0
	v_add_f32_e32 v3, v3, v60
	v_add_f32_e32 v3, v3, v61
	ds_bpermute_b32 v54, v18, v3
	s_waitcnt lgkmcnt(0)
	v_add_f32_e32 v3, v3, v54
	ds_bpermute_b32 v54, v19, v3
	s_waitcnt lgkmcnt(0)
	v_add_f32_e32 v3, v3, v54
	ds_bpermute_b32 v54, v20, v3
	s_waitcnt lgkmcnt(0)
	v_add_f32_e32 v3, v3, v54
	ds_bpermute_b32 v54, v21, v3
	s_waitcnt lgkmcnt(0)
	v_add_f32_e32 v3, v3, v54
	ds_bpermute_b32 v54, v22, v3
	s_waitcnt lgkmcnt(0)
	v_add_f32_e32 v3, v3, v54
	ds_bpermute_b32 v54, v23, v3
	s_waitcnt lgkmcnt(0)
	v_add_f32_e32 v3, v3, v54
	v_fmamk_f32 v3, v3, 0x3a800000, v225
	v_cmp_gt_f32_e32 vcc, s85, v3
	v_mul_f32_e32 v54, 0x4b800000, v3
	s_nop 0
	v_cndmask_b32_e32 v3, v3, v54, vcc
	v_rsq_f32_e32 v3, v3
	s_nop 0
	v_mul_f32_e32 v54, 0x45800000, v3
	v_cndmask_b32_e32 v54, v3, v54, vcc
	v_pk_mul_f32 v[24:25], v[24:25], v[54:55] op_sel_hi:[1,0]
	v_pk_mul_f32 v[26:27], v[26:27], v[54:55] op_sel_hi:[1,0]
	v_pk_mul_f32 v[24:25], v[28:29], v[24:25]
	v_pk_mul_f32 v[26:27], v[30:31], v[26:27]
	v_pk_fma_f32 v[24:25], v[50:51], v[24:25], v[36:37]
	v_pk_fma_f32 v[26:27], v[48:49], v[26:27], v[38:39]
	v_cvt_pk_bf16_f32 v24, v24, v25
	v_cvt_pk_bf16_f32 v25, v26, v27
	global_store_dwordx2 v[8:9], v[24:25], off offset:-1024
	s_nop 0
	v_pk_mul_f32 v[72:73], v[72:73], v[54:55] op_sel_hi:[1,0]
	v_cmp_lt_i32_e32 vcc, s91, v2
	s_or_b64 s[2:3], vcc, s[2:3]
	s_waitcnt vmcnt(7)
	v_pk_mul_f32 v[84:85], v[72:73], v[84:85]
	v_pk_add_f32 v[88:89], v[88:89], 1.0 op_sel_hi:[1,0]
	v_pk_fma_f32 v[84:85], v[84:85], v[88:89], v[92:93]
	v_pk_mul_f32 v[88:89], v[74:75], v[54:55] op_sel_hi:[1,0]
	v_cvt_pk_bf16_f32 v84, v84, v85
	v_pk_mul_f32 v[86:87], v[88:89], v[86:87]
	v_pk_add_f32 v[88:89], v[90:91], 1.0 op_sel_hi:[1,0]
	v_pk_mul_f32 v[92:93], v[80:81], v[54:55] op_sel_hi:[1,0]
	v_pk_fma_f32 v[86:87], v[86:87], v[88:89], v[94:95]
	s_nop 0
	v_cvt_pk_bf16_f32 v85, v86, v87
	global_store_dwordx2 v[8:9], v[84:85], off offset:-512
	s_nop 0
	s_waitcnt vmcnt(5)
	v_pk_mul_f32 v[96:97], v[92:93], v[96:97]
	v_pk_add_f32 v[100:101], v[100:101], 1.0 op_sel_hi:[1,0]
	v_pk_fma_f32 v[96:97], v[96:97], v[100:101], v[104:105]
	v_pk_mul_f32 v[100:101], v[82:83], v[54:55] op_sel_hi:[1,0]
	v_cvt_pk_bf16_f32 v96, v96, v97
	v_pk_mul_f32 v[98:99], v[100:101], v[98:99]
	v_pk_add_f32 v[100:101], v[102:103], 1.0 op_sel_hi:[1,0]
	s_nop 0
	v_pk_fma_f32 v[98:99], v[98:99], v[100:101], v[106:107]
	s_nop 0
	v_cvt_pk_bf16_f32 v97, v98, v99
	global_store_dwordx2 v[8:9], v[96:97], off
	s_nop 0
	v_pk_mul_f32 v[16:17], v[76:77], v[54:55] op_sel_hi:[1,0]
	s_waitcnt vmcnt(3)
	v_pk_mul_f32 v[16:17], v[16:17], v[108:109]
	v_pk_add_f32 v[108:109], v[112:113], 1.0 op_sel_hi:[1,0]
	v_pk_fma_f32 v[16:17], v[16:17], v[108:109], v[116:117]
	v_pk_mul_f32 v[108:109], v[78:79], v[54:55] op_sel_hi:[1,0]
	v_cvt_pk_bf16_f32 v16, v16, v17
	v_pk_mul_f32 v[108:109], v[108:109], v[110:111]
	v_pk_add_f32 v[110:111], v[114:115], 1.0 op_sel_hi:[1,0]
	s_nop 0
	v_pk_fma_f32 v[108:109], v[108:109], v[110:111], v[118:119]
	s_nop 0
	v_cvt_pk_bf16_f32 v17, v108, v109
	global_store_dwordx2 v[8:9], v[16:17], off offset:512
	v_lshl_add_u64 v[8:9], v[8:9], 0, s[68:69]
	s_andn2_b64 exec, exec, s[2:3]
	s_cbranch_execnz .LBB0_369

; DI void phase_inproj(const Prm& p, unsigned char* smem_raw, int l, int S, int& base) {
;     ...
;                 if (nb == 4160) {
;                   const f32x4 v2 = acc[ai][bj][(m + 1) & 3][n];
;                   const int pos = tok & (S - 1);
; #pragma unroll
;                   for (int j = 0; j < 4; ++j) {
;                     const int ii = fq * 4 + j;
;                     const float2 cs = p.rope[pos * 16 + ii];
;                     const u16 o1 = f2bf(v[j] * cs.x - v2[j] * cs.y), o2 = f2bf(v[j] * cs.y + v2[j] * cs.x);
; #pragma unroll
;                     for (int hh = 0; hh < 4; ++hh) {
;                       p.kc[(size_t)tok * 384 + hh * 96 + 64 + ii] = o1;
;                       p.kc[(size_t)tok * 384 + hh * 96 + 80 + ii] = o2;
;                     }
;                   }
.LBB0_605:
	s_andn2_b64 vcc, exec, s[2:3]
	s_cbranch_vccnz .LBB0_608
	s_andn2_b64 vcc, exec, s[4:5]
	s_cbranch_vccnz .LBB0_608
	v_readlane_b32 s36, v252, 0
	v_readlane_b32 s2, v254, 45
	v_readlane_b32 s37, v252, 1
	v_readlane_b32 s38, v252, 2
	v_readlane_b32 s39, v252, 3
	v_readlane_b32 s40, v252, 4
	v_readlane_b32 s41, v252, 5
	v_readlane_b32 s42, v252, 6
	v_readlane_b32 s43, v252, 7
	v_and_b32_e32 v131, s2, v130
	v_mov_b64_e32 v[134:135], s[36:37]
	v_readlane_b32 s36, v253, 8
	v_lshl_or_b32 v136, v131, 4, v132
	v_mov_b32_e32 v137, v1
	v_readlane_b32 s40, v253, 12
	v_readlane_b32 s41, v253, 13
	v_mad_i64_i32 v[134:135], s[2:3], v130, s33, v[134:135]
	s_nop 0
	v_lshl_add_u64 v[136:137], v[136:137], 3, s[40:41]
	global_load_dwordx2 v[144:145], v[136:137], off
	global_load_dwordx2 v[146:147], v[136:137], off offset:8
	global_load_dwordx2 v[148:149], v[136:137], off offset:16
	global_load_dwordx2 v[150:151], v[136:137], off offset:24
	v_readlane_b32 s37, v253, 9
	v_readlane_b32 s38, v253, 10
	v_readlane_b32 s39, v253, 11
	v_readlane_b32 s42, v253, 14
	v_readlane_b32 s43, v253, 15
	v_readlane_b32 s44, v253, 16
	v_readlane_b32 s45, v253, 17
	v_readlane_b32 s46, v253, 18
	v_readlane_b32 s47, v253, 19
	v_readlane_b32 s48, v253, 20
	v_readlane_b32 s49, v253, 21
	v_readlane_b32 s50, v253, 22
	v_readlane_b32 s51, v253, 23
	s_waitcnt vmcnt(0)
	v_mul_f32_e32 v131, v110, v145
	v_mul_f32_e32 v145, v126, v145
	v_fmac_f32_e32 v145, v110, v144
	v_fma_f32 v131, v126, v144, -v131
	v_cvt_pk_bf16_f32 v140, v145, s0
	v_lshlrev_b32_e32 v144, 1, v132
	v_mov_b32_e32 v145, v1
	v_cvt_pk_bf16_f32 v131, v131, s0
	v_lshl_add_u64 v[134:135], v[134:135], 0, v[144:145]
	global_store_short v[134:135], v131, off offset:128
	global_store_short v[134:135], v140, off offset:160
	global_store_short v[134:135], v131, off offset:320
	global_store_short v[134:135], v140, off offset:352
	global_store_short v[134:135], v131, off offset:512
	global_store_short v[134:135], v140, off offset:544
	global_store_short v[134:135], v131, off offset:704
	global_store_short v[134:135], v140, off offset:736
	v_mul_f32_e32 v131, v111, v147
	v_fma_f32 v131, v127, v146, -v131
	v_mul_f32_e32 v147, v127, v147
	v_cvt_pk_bf16_f32 v131, v131, s0
	v_fmac_f32_e32 v147, v111, v146
	v_cvt_pk_bf16_f32 v146, v147, s0
	global_store_short v[134:135], v131, off offset:130
	global_store_short v[134:135], v146, off offset:162
	global_store_short v[134:135], v131, off offset:322
	global_store_short v[134:135], v146, off offset:354
	global_store_short v[134:135], v131, off offset:514
	global_store_short v[134:135], v146, off offset:546
	global_store_short v[134:135], v131, off offset:706
	global_store_short v[134:135], v146, off offset:738
	v_mul_f32_e32 v131, v112, v149
	v_fma_f32 v131, v128, v148, -v131
	v_mul_f32_e32 v149, v128, v149
	v_cvt_pk_bf16_f32 v131, v131, s0
	v_fmac_f32_e32 v149, v112, v148
	v_cvt_pk_bf16_f32 v148, v149, s0
	global_store_short v[134:135], v131, off offset:132
	global_store_short v[134:135], v148, off offset:164
	global_store_short v[134:135], v131, off offset:324
	global_store_short v[134:135], v148, off offset:356
	global_store_short v[134:135], v131, off offset:516
	global_store_short v[134:135], v148, off offset:548
	global_store_short v[134:135], v131, off offset:708
	global_store_short v[134:135], v148, off offset:740
	v_mul_f32_e32 v131, v113, v151
	v_fma_f32 v131, v129, v150, -v131
	v_mul_f32_e32 v151, v129, v151
	v_cvt_pk_bf16_f32 v131, v131, s0
	v_fmac_f32_e32 v151, v113, v150
	v_cvt_pk_bf16_f32 v150, v151, s0
	global_store_short v[134:135], v131, off offset:134
	global_store_short v[134:135], v150, off offset:166
	global_store_short v[134:135], v131, off offset:326
	global_store_short v[134:135], v150, off offset:358
	global_store_short v[134:135], v131, off offset:518
	global_store_short v[134:135], v150, off offset:550
	global_store_short v[134:135], v131, off offset:710
	global_store_short v[134:135], v150, off offset:742

; DI void phase_inproj(const Prm& p, unsigned char* smem_raw, int l, int S, int& base) {
;     ...
;                 if (nb == 4160) {
;                   const f32x4 v2 = acc[ai][bj][(m + 1) & 3][n];
;                   const int pos = tok & (S - 1);
; #pragma unroll
;                   for (int j = 0; j < 4; ++j) {
;                     const int ii = fq * 4 + j;
;                     const float2 cs = p.rope[pos * 16 + ii];
;                     const u16 o1 = f2bf(v[j] * cs.x - v2[j] * cs.y), o2 = f2bf(v[j] * cs.y + v2[j] * cs.x);
; #pragma unroll
;                     for (int hh = 0; hh < 4; ++hh) {
;                       p.kc[(size_t)tok * 384 + hh * 96 + 64 + ii] = o1;
;                       p.kc[(size_t)tok * 384 + hh * 96 + 80 + ii] = o2;
;                     }
;                   }
.LBB0_639:
	s_andn2_b64 vcc, exec, s[0:1]
	s_cbranch_vccnz .LBB0_642
	s_andn2_b64 vcc, exec, s[4:5]
	s_cbranch_vccnz .LBB0_642
	v_readlane_b32 s0, v254, 45
	v_mov_b32_e32 v125, v1
	s_nop 0
	v_and_b32_e32 v119, s0, v118
	v_readlane_b32 s0, v252, 0
	v_readlane_b32 s1, v252, 1
	v_readlane_b32 s2, v252, 2
	v_readlane_b32 s3, v252, 3
	v_mov_b64_e32 v[120:121], s[0:1]
	v_readlane_b32 s4, v252, 4
	v_readlane_b32 s5, v252, 5
	v_readlane_b32 s6, v252, 6
	v_readlane_b32 s7, v252, 7
	v_mad_i64_i32 v[120:121], s[0:1], v118, s33, v[120:121]
	v_readlane_b32 s0, v253, 8
	v_lshl_or_b32 v124, v119, 4, v132
	v_readlane_b32 s4, v253, 12
	v_readlane_b32 s5, v253, 13
	v_readlane_b32 s1, v253, 9
	v_readlane_b32 s2, v253, 10
	v_lshl_add_u64 v[124:125], v[124:125], 3, s[4:5]
	global_load_dwordx2 v[144:145], v[124:125], off
	global_load_dwordx2 v[146:147], v[124:125], off offset:8
	global_load_dwordx2 v[148:149], v[124:125], off offset:16
	global_load_dwordx2 v[150:151], v[124:125], off offset:24
	v_readlane_b32 s3, v253, 11
	v_readlane_b32 s6, v253, 14
	v_readlane_b32 s7, v253, 15
	v_readlane_b32 s8, v253, 16
	v_readlane_b32 s9, v253, 17
	v_readlane_b32 s10, v253, 18
	v_readlane_b32 s11, v253, 19
	v_readlane_b32 s12, v253, 20
	v_readlane_b32 s13, v253, 21
	v_readlane_b32 s14, v253, 22
	v_readlane_b32 s15, v253, 23
	s_waitcnt vmcnt(0)
	v_mul_f32_e32 v119, v98, v145
	v_mul_f32_e32 v123, v114, v145
	v_fma_f32 v119, v114, v144, -v119
	v_fmac_f32_e32 v123, v98, v144
	v_lshlrev_b32_e32 v144, 1, v132
	v_mov_b32_e32 v145, v1
	v_cvt_pk_bf16_f32 v119, v119, s0
	v_lshl_add_u64 v[120:121], v[120:121], 0, v[144:145]
	v_cvt_pk_bf16_f32 v123, v123, s0
	global_store_short v[120:121], v119, off offset:128
	global_store_short v[120:121], v123, off offset:160
	global_store_short v[120:121], v119, off offset:320
	global_store_short v[120:121], v123, off offset:352
	global_store_short v[120:121], v119, off offset:512
	global_store_short v[120:121], v123, off offset:544
	global_store_short v[120:121], v119, off offset:704
	global_store_short v[120:121], v123, off offset:736
	v_mul_f32_e32 v119, v99, v147
	v_fma_f32 v119, v115, v146, -v119
	v_mul_f32_e32 v123, v115, v147
	v_cvt_pk_bf16_f32 v119, v119, s0
	v_fmac_f32_e32 v123, v99, v146
	v_cvt_pk_bf16_f32 v123, v123, s0
	global_store_short v[120:121], v119, off offset:130
	global_store_short v[120:121], v123, off offset:162
	global_store_short v[120:121], v119, off offset:322
	global_store_short v[120:121], v123, off offset:354
	global_store_short v[120:121], v119, off offset:514
	global_store_short v[120:121], v123, off offset:546
	global_store_short v[120:121], v119, off offset:706
	global_store_short v[120:121], v123, off offset:738
	v_mul_f32_e32 v119, v100, v149
	v_fma_f32 v119, v116, v148, -v119
	v_mul_f32_e32 v123, v116, v149
	v_cvt_pk_bf16_f32 v119, v119, s0
	v_fmac_f32_e32 v123, v100, v148
	v_cvt_pk_bf16_f32 v123, v123, s0
	global_store_short v[120:121], v119, off offset:132
	global_store_short v[120:121], v123, off offset:164
	global_store_short v[120:121], v119, off offset:324
	global_store_short v[120:121], v123, off offset:356
	global_store_short v[120:121], v119, off offset:516
	global_store_short v[120:121], v123, off offset:548
	global_store_short v[120:121], v119, off offset:708
	global_store_short v[120:121], v123, off offset:740
	v_mul_f32_e32 v119, v101, v151
	v_fma_f32 v119, v117, v150, -v119
	v_mul_f32_e32 v123, v117, v151
	v_cvt_pk_bf16_f32 v119, v119, s0
	v_fmac_f32_e32 v123, v101, v150
	v_cvt_pk_bf16_f32 v123, v123, s0
	global_store_short v[120:121], v119, off offset:134
	global_store_short v[120:121], v123, off offset:166
	global_store_short v[120:121], v119, off offset:326
	global_store_short v[120:121], v123, off offset:358
	global_store_short v[120:121], v119, off offset:518
	global_store_short v[120:121], v123, off offset:550
	global_store_short v[120:121], v119, off offset:710
	global_store_short v[120:121], v123, off offset:742

; DI void phase_inproj(const Prm& p, unsigned char* smem_raw, int l, int S, int& base) {
;     ...
;                 if (nb == 4160) {
;                   const f32x4 v2 = acc[ai][bj][(m + 1) & 3][n];
;                   const int pos = tok & (S - 1);
; #pragma unroll
;                   for (int j = 0; j < 4; ++j) {
;                     const int ii = fq * 4 + j;
;                     const float2 cs = p.rope[pos * 16 + ii];
;                     const u16 o1 = f2bf(v[j] * cs.x - v2[j] * cs.y), o2 = f2bf(v[j] * cs.y + v2[j] * cs.x);
; #pragma unroll
;                     for (int hh = 0; hh < 4; ++hh) {
;                       p.kc[(size_t)tok * 384 + hh * 96 + 64 + ii] = o1;
;                       p.kc[(size_t)tok * 384 + hh * 96 + 80 + ii] = o2;
;                     }
;                   }
.LBB0_767:
	s_andn2_b64 vcc, exec, s[0:1]
	s_cbranch_vccnz .LBB0_770
	s_andn2_b64 vcc, exec, s[4:5]
	s_cbranch_vccnz .LBB0_770
	v_readlane_b32 s36, v252, 0
	v_readlane_b32 s0, v254, 45
	v_readlane_b32 s37, v252, 1
	v_readlane_b32 s38, v252, 2
	v_readlane_b32 s39, v252, 3
	v_readlane_b32 s40, v252, 4
	v_readlane_b32 s41, v252, 5
	v_readlane_b32 s42, v252, 6
	v_readlane_b32 s43, v252, 7
	v_and_b32_e32 v67, s0, v130
	v_mov_b64_e32 v[68:69], s[36:37]
	v_readlane_b32 s36, v253, 8
	v_lshl_or_b32 v70, v67, 4, v132
	v_mov_b32_e32 v71, v1
	v_readlane_b32 s40, v253, 12
	v_readlane_b32 s41, v253, 13
	v_mad_i64_i32 v[68:69], s[0:1], v130, s33, v[68:69]
	s_nop 0
	v_lshl_add_u64 v[70:71], v[70:71], 3, s[40:41]
	global_load_dwordx2 v[144:145], v[70:71], off
	global_load_dwordx2 v[146:147], v[70:71], off offset:8
	global_load_dwordx2 v[148:149], v[70:71], off offset:16
	global_load_dwordx2 v[150:151], v[70:71], off offset:24
	v_readlane_b32 s37, v253, 9
	v_readlane_b32 s38, v253, 10
	v_readlane_b32 s39, v253, 11
	v_readlane_b32 s42, v253, 14
	v_readlane_b32 s43, v253, 15
	v_readlane_b32 s44, v253, 16
	v_readlane_b32 s45, v253, 17
	v_readlane_b32 s46, v253, 18
	v_readlane_b32 s47, v253, 19
	v_readlane_b32 s48, v253, 20
	v_readlane_b32 s49, v253, 21
	v_readlane_b32 s50, v253, 22
	v_readlane_b32 s51, v253, 23
	s_waitcnt vmcnt(0)
	v_mul_f32_e32 v67, v46, v145
	v_mul_f32_e32 v145, v62, v145
	v_fmac_f32_e32 v145, v46, v144
	v_fma_f32 v67, v62, v144, -v67
	v_cvt_pk_bf16_f32 v74, v145, s0
	v_lshlrev_b32_e32 v144, 1, v132
	v_mov_b32_e32 v145, v1
	v_cvt_pk_bf16_f32 v67, v67, s0
	v_lshl_add_u64 v[68:69], v[68:69], 0, v[144:145]
	global_store_short v[68:69], v67, off offset:128
	global_store_short v[68:69], v74, off offset:160
	global_store_short v[68:69], v67, off offset:320
	global_store_short v[68:69], v74, off offset:352
	global_store_short v[68:69], v67, off offset:512
	global_store_short v[68:69], v74, off offset:544
	global_store_short v[68:69], v67, off offset:704
	global_store_short v[68:69], v74, off offset:736
	v_mul_f32_e32 v67, v47, v147
	v_fma_f32 v67, v63, v146, -v67
	v_mul_f32_e32 v147, v63, v147
	v_cvt_pk_bf16_f32 v67, v67, s0
	v_fmac_f32_e32 v147, v47, v146
	v_cvt_pk_bf16_f32 v146, v147, s0
	global_store_short v[68:69], v67, off offset:130
	global_store_short v[68:69], v146, off offset:162
	global_store_short v[68:69], v67, off offset:322
	global_store_short v[68:69], v146, off offset:354
	global_store_short v[68:69], v67, off offset:514
	global_store_short v[68:69], v146, off offset:546
	global_store_short v[68:69], v67, off offset:706
	global_store_short v[68:69], v146, off offset:738
	v_mul_f32_e32 v67, v48, v149
	v_fma_f32 v67, v64, v148, -v67
	v_mul_f32_e32 v149, v64, v149
	v_cvt_pk_bf16_f32 v67, v67, s0
	v_fmac_f32_e32 v149, v48, v148
	v_cvt_pk_bf16_f32 v148, v149, s0
	global_store_short v[68:69], v67, off offset:132
	global_store_short v[68:69], v148, off offset:164
	global_store_short v[68:69], v67, off offset:324
	global_store_short v[68:69], v148, off offset:356
	global_store_short v[68:69], v67, off offset:516
	global_store_short v[68:69], v148, off offset:548
	global_store_short v[68:69], v67, off offset:708
	global_store_short v[68:69], v148, off offset:740
	v_mul_f32_e32 v67, v49, v151
	v_fma_f32 v67, v65, v150, -v67
	v_mul_f32_e32 v151, v65, v151
	v_cvt_pk_bf16_f32 v67, v67, s0
	v_fmac_f32_e32 v151, v49, v150
	v_cvt_pk_bf16_f32 v150, v151, s0
	global_store_short v[68:69], v67, off offset:134
	global_store_short v[68:69], v150, off offset:166
	global_store_short v[68:69], v67, off offset:326
	global_store_short v[68:69], v150, off offset:358
	global_store_short v[68:69], v67, off offset:518
	global_store_short v[68:69], v150, off offset:550
	global_store_short v[68:69], v67, off offset:710
	global_store_short v[68:69], v150, off offset:742

; DI void phase_inproj(const Prm& p, unsigned char* smem_raw, int l, int S, int& base) {
;     ...
;                 if (nb == 4160) {
;                   const f32x4 v2 = acc[ai][bj][(m + 1) & 3][n];
;                   const int pos = tok & (S - 1);
; #pragma unroll
;                   for (int j = 0; j < 4; ++j) {
;                     const int ii = fq * 4 + j;
;                     const float2 cs = p.rope[pos * 16 + ii];
;                     const u16 o1 = f2bf(v[j] * cs.x - v2[j] * cs.y), o2 = f2bf(v[j] * cs.y + v2[j] * cs.x);
; #pragma unroll
;                     for (int hh = 0; hh < 4; ++hh) {
;                       p.kc[(size_t)tok * 384 + hh * 96 + 64 + ii] = o1;
;                       p.kc[(size_t)tok * 384 + hh * 96 + 80 + ii] = o2;
;                     }
;                   }
.LBB0_1135:
	s_andn2_b64 vcc, exec, s[52:53]
	s_cbranch_vccnz .LBB0_1138
	s_andn2_b64 vcc, exec, s[4:5]
	s_cbranch_vccnz .LBB0_1138
	v_readlane_b32 s36, v252, 0
	v_readlane_b32 s8, v254, 45
	v_readlane_b32 s37, v252, 1
	v_readlane_b32 s38, v252, 2
	v_readlane_b32 s39, v252, 3
	v_readlane_b32 s40, v252, 4
	v_readlane_b32 s41, v252, 5
	v_readlane_b32 s42, v252, 6
	v_readlane_b32 s43, v252, 7
	v_and_b32_e32 v127, s8, v126
	v_mov_b64_e32 v[128:129], s[36:37]
	v_readlane_b32 s36, v253, 8
	v_lshl_or_b32 v138, v127, 4, v132
	v_mov_b32_e32 v139, v1
	v_readlane_b32 s40, v253, 12
	v_readlane_b32 s41, v253, 13
	v_mad_i64_i32 v[128:129], s[52:53], v126, s33, v[128:129]
	s_nop 0
	v_lshl_add_u64 v[138:139], v[138:139], 3, s[40:41]
	global_load_dwordx2 v[144:145], v[138:139], off
	global_load_dwordx2 v[146:147], v[138:139], off offset:8
	global_load_dwordx2 v[148:149], v[138:139], off offset:16
	global_load_dwordx2 v[150:151], v[138:139], off offset:24
	v_readlane_b32 s37, v253, 9
	v_readlane_b32 s38, v253, 10
	v_readlane_b32 s39, v253, 11
	v_readlane_b32 s42, v253, 14
	v_readlane_b32 s43, v253, 15
	v_readlane_b32 s44, v253, 16
	v_readlane_b32 s45, v253, 17
	v_readlane_b32 s46, v253, 18
	v_readlane_b32 s47, v253, 19
	v_readlane_b32 s48, v253, 20
	v_readlane_b32 s49, v253, 21
	v_readlane_b32 s50, v253, 22
	v_readlane_b32 s51, v253, 23
	s_waitcnt vmcnt(0)
	v_mul_f32_e32 v127, v106, v145
	v_mul_f32_e32 v137, v122, v145
	v_fma_f32 v127, v122, v144, -v127
	v_fmac_f32_e32 v137, v106, v144
	v_lshlrev_b32_e32 v144, 1, v132
	v_mov_b32_e32 v145, v1
	v_cvt_pk_bf16_f32 v127, v127, s0
	v_lshl_add_u64 v[128:129], v[128:129], 0, v[144:145]
	v_cvt_pk_bf16_f32 v137, v137, s0
	global_store_short v[128:129], v127, off offset:128
	global_store_short v[128:129], v137, off offset:160
	global_store_short v[128:129], v127, off offset:320
	global_store_short v[128:129], v137, off offset:352
	global_store_short v[128:129], v127, off offset:512
	global_store_short v[128:129], v137, off offset:544
	global_store_short v[128:129], v127, off offset:704
	global_store_short v[128:129], v137, off offset:736
	v_mul_f32_e32 v127, v107, v147
	v_fma_f32 v127, v123, v146, -v127
	v_mul_f32_e32 v137, v123, v147
	v_cvt_pk_bf16_f32 v127, v127, s0
	v_fmac_f32_e32 v137, v107, v146
	v_cvt_pk_bf16_f32 v137, v137, s0
	global_store_short v[128:129], v127, off offset:130
	global_store_short v[128:129], v137, off offset:162
	global_store_short v[128:129], v127, off offset:322
	global_store_short v[128:129], v137, off offset:354
	global_store_short v[128:129], v127, off offset:514
	global_store_short v[128:129], v137, off offset:546
	global_store_short v[128:129], v127, off offset:706
	global_store_short v[128:129], v137, off offset:738
	v_mul_f32_e32 v127, v108, v149
	v_fma_f32 v127, v124, v148, -v127
	v_mul_f32_e32 v137, v124, v149
	v_cvt_pk_bf16_f32 v127, v127, s0
	v_fmac_f32_e32 v137, v108, v148
	v_cvt_pk_bf16_f32 v137, v137, s0
	global_store_short v[128:129], v127, off offset:132
	global_store_short v[128:129], v137, off offset:164
	global_store_short v[128:129], v127, off offset:324
	global_store_short v[128:129], v137, off offset:356
	global_store_short v[128:129], v127, off offset:516
	global_store_short v[128:129], v137, off offset:548
	global_store_short v[128:129], v127, off offset:708
	global_store_short v[128:129], v137, off offset:740
	v_mul_f32_e32 v127, v109, v151
	v_fma_f32 v127, v125, v150, -v127
	v_mul_f32_e32 v137, v125, v151
	v_cvt_pk_bf16_f32 v127, v127, s0
	v_fmac_f32_e32 v137, v109, v150
	v_cvt_pk_bf16_f32 v137, v137, s0
	global_store_short v[128:129], v127, off offset:134
	global_store_short v[128:129], v137, off offset:166
	global_store_short v[128:129], v127, off offset:326
	global_store_short v[128:129], v137, off offset:358
	global_store_short v[128:129], v127, off offset:518
	global_store_short v[128:129], v137, off offset:550
	global_store_short v[128:129], v127, off offset:710
	global_store_short v[128:129], v137, off offset:742

; DI void phase_inproj(const Prm& p, unsigned char* smem_raw, int l, int S, int& base) {
;     ...
;                 if (nb == 4160) {
;                   const f32x4 v2 = acc[ai][bj][(m + 1) & 3][n];
;                   const int pos = tok & (S - 1);
; #pragma unroll
;                   for (int j = 0; j < 4; ++j) {
;                     const int ii = fq * 4 + j;
;                     const float2 cs = p.rope[pos * 16 + ii];
;                     const u16 o1 = f2bf(v[j] * cs.x - v2[j] * cs.y), o2 = f2bf(v[j] * cs.y + v2[j] * cs.x);
; #pragma unroll
;                     for (int hh = 0; hh < 4; ++hh) {
;                       p.kc[(size_t)tok * 384 + hh * 96 + 64 + ii] = o1;
;                       p.kc[(size_t)tok * 384 + hh * 96 + 80 + ii] = o2;
;                     }
;                   }
;                 }
.LBB0_1162:
	s_andn2_b64 vcc, exec, s[52:53]
	s_cbranch_vccnz .LBB0_1165
	s_andn2_b64 vcc, exec, s[4:5]
	s_cbranch_vccnz .LBB0_1165
	v_readlane_b32 s36, v252, 0
	v_readlane_b32 s8, v254, 45
	v_readlane_b32 s37, v252, 1
	v_readlane_b32 s38, v252, 2
	v_readlane_b32 s39, v252, 3
	v_readlane_b32 s40, v252, 4
	v_readlane_b32 s41, v252, 5
	v_readlane_b32 s42, v252, 6
	v_readlane_b32 s43, v252, 7
	v_and_b32_e32 v123, s8, v122
	v_mov_b64_e32 v[124:125], s[36:37]
	v_readlane_b32 s36, v253, 8
	v_lshl_or_b32 v128, v123, 4, v132
	v_mov_b32_e32 v129, v1
	v_readlane_b32 s40, v253, 12
	v_readlane_b32 s41, v253, 13
	v_mad_i64_i32 v[124:125], s[52:53], v122, s33, v[124:125]
	s_nop 0
	v_lshl_add_u64 v[128:129], v[128:129], 3, s[40:41]
	global_load_dwordx2 v[144:145], v[128:129], off
	global_load_dwordx2 v[146:147], v[128:129], off offset:8
	global_load_dwordx2 v[148:149], v[128:129], off offset:16
	global_load_dwordx2 v[150:151], v[128:129], off offset:24
	v_readlane_b32 s37, v253, 9
	v_readlane_b32 s38, v253, 10
	v_readlane_b32 s39, v253, 11
	v_readlane_b32 s42, v253, 14
	v_readlane_b32 s43, v253, 15
	v_readlane_b32 s44, v253, 16
	v_readlane_b32 s45, v253, 17
	v_readlane_b32 s46, v253, 18
	v_readlane_b32 s47, v253, 19
	v_readlane_b32 s48, v253, 20
	v_readlane_b32 s49, v253, 21
	v_readlane_b32 s50, v253, 22
	v_readlane_b32 s51, v253, 23
	s_waitcnt vmcnt(0)
	v_mul_f32_e32 v123, v102, v145
	v_mul_f32_e32 v127, v118, v145
	v_fma_f32 v123, v118, v144, -v123
	v_fmac_f32_e32 v127, v102, v144
	v_lshlrev_b32_e32 v144, 1, v132
	v_mov_b32_e32 v145, v1
	v_cvt_pk_bf16_f32 v123, v123, s0
	v_lshl_add_u64 v[124:125], v[124:125], 0, v[144:145]
	v_cvt_pk_bf16_f32 v127, v127, s0
	global_store_short v[124:125], v123, off offset:128
	global_store_short v[124:125], v127, off offset:160
	global_store_short v[124:125], v123, off offset:320
	global_store_short v[124:125], v127, off offset:352
	global_store_short v[124:125], v123, off offset:512
	global_store_short v[124:125], v127, off offset:544
	global_store_short v[124:125], v123, off offset:704
	global_store_short v[124:125], v127, off offset:736
	v_mul_f32_e32 v123, v103, v147
	v_fma_f32 v123, v119, v146, -v123
	v_mul_f32_e32 v127, v119, v147
	v_cvt_pk_bf16_f32 v123, v123, s0
	v_fmac_f32_e32 v127, v103, v146
	v_cvt_pk_bf16_f32 v127, v127, s0
	global_store_short v[124:125], v123, off offset:130
	global_store_short v[124:125], v127, off offset:162
	global_store_short v[124:125], v123, off offset:322
	global_store_short v[124:125], v127, off offset:354
	global_store_short v[124:125], v123, off offset:514
	global_store_short v[124:125], v127, off offset:546
	global_store_short v[124:125], v123, off offset:706
	global_store_short v[124:125], v127, off offset:738
	v_mul_f32_e32 v123, v104, v149
	v_fma_f32 v123, v120, v148, -v123
	v_mul_f32_e32 v127, v120, v149
	v_cvt_pk_bf16_f32 v123, v123, s0
	v_fmac_f32_e32 v127, v104, v148
	v_cvt_pk_bf16_f32 v127, v127, s0
	global_store_short v[124:125], v123, off offset:132
	global_store_short v[124:125], v127, off offset:164
	global_store_short v[124:125], v123, off offset:324
	global_store_short v[124:125], v127, off offset:356
	global_store_short v[124:125], v123, off offset:516
	global_store_short v[124:125], v127, off offset:548
	global_store_short v[124:125], v123, off offset:708
	global_store_short v[124:125], v127, off offset:740
	v_mul_f32_e32 v123, v105, v151
	v_fma_f32 v123, v121, v150, -v123
	v_mul_f32_e32 v127, v121, v151
	v_cvt_pk_bf16_f32 v123, v123, s0
	v_fmac_f32_e32 v127, v105, v150
	v_cvt_pk_bf16_f32 v127, v127, s0
	global_store_short v[124:125], v123, off offset:134
	global_store_short v[124:125], v127, off offset:166
	global_store_short v[124:125], v123, off offset:326
	global_store_short v[124:125], v127, off offset:358
	global_store_short v[124:125], v123, off offset:518
	global_store_short v[124:125], v127, off offset:550
	global_store_short v[124:125], v123, off offset:710
	global_store_short v[124:125], v127, off offset:742

; DI void phase_inproj(const Prm& p, unsigned char* smem_raw, int l, int S, int& base) {
;     ...
;                 if (nb == 4160) {
;                   const f32x4 v2 = acc[ai][bj][(m + 1) & 3][n];
;                   const int pos = tok & (S - 1);
; #pragma unroll
;                   for (int j = 0; j < 4; ++j) {
;                     const int ii = fq * 4 + j;
;                     const float2 cs = p.rope[pos * 16 + ii];
;                     const u16 o1 = f2bf(v[j] * cs.x - v2[j] * cs.y), o2 = f2bf(v[j] * cs.y + v2[j] * cs.x);
; #pragma unroll
;                     for (int hh = 0; hh < 4; ++hh) {
;                       p.kc[(size_t)tok * 384 + hh * 96 + 64 + ii] = o1;
;                       p.kc[(size_t)tok * 384 + hh * 96 + 80 + ii] = o2;
;                     }
;                   }
;                 }
.LBB0_1401:
	s_andn2_b64 vcc, exec, s[54:55]
	s_cbranch_vccnz .LBB0_1404
	s_andn2_b64 vcc, exec, s[4:5]
	s_cbranch_vccnz .LBB0_1404
	v_readlane_b32 s36, v252, 0
	v_readlane_b32 s8, v254, 45
	v_readlane_b32 s37, v252, 1
	v_readlane_b32 s38, v252, 2
	v_readlane_b32 s39, v252, 3
	v_readlane_b32 s40, v252, 4
	v_readlane_b32 s41, v252, 5
	v_readlane_b32 s42, v252, 6
	v_readlane_b32 s43, v252, 7
	v_and_b32_e32 v64, s8, v126
	v_mov_b64_e32 v[62:63], s[36:37]
	v_readlane_b32 s36, v253, 8
	v_lshl_or_b32 v64, v64, 4, v132
	v_mov_b32_e32 v65, v1
	v_readlane_b32 s40, v253, 12
	v_readlane_b32 s41, v253, 13
	v_mad_i64_i32 v[62:63], s[54:55], v126, s33, v[62:63]
	s_nop 0
	v_lshl_add_u64 v[64:65], v[64:65], 3, s[40:41]
	global_load_dwordx2 v[144:145], v[64:65], off
	global_load_dwordx2 v[146:147], v[64:65], off offset:8
	global_load_dwordx2 v[148:149], v[64:65], off offset:16
	global_load_dwordx2 v[150:151], v[64:65], off offset:24
	v_readlane_b32 s37, v253, 9
	v_readlane_b32 s38, v253, 10
	v_readlane_b32 s39, v253, 11
	v_readlane_b32 s42, v253, 14
	v_readlane_b32 s43, v253, 15
	v_readlane_b32 s44, v253, 16
	v_readlane_b32 s45, v253, 17
	v_readlane_b32 s46, v253, 18
	v_readlane_b32 s47, v253, 19
	v_readlane_b32 s48, v253, 20
	v_readlane_b32 s49, v253, 21
	v_readlane_b32 s50, v253, 22
	v_readlane_b32 s51, v253, 23
	s_waitcnt vmcnt(0)
	v_mul_f32_e32 v72, v42, v145
	v_mul_f32_e32 v145, v58, v145
	v_fmac_f32_e32 v145, v42, v144
	v_fma_f32 v72, v58, v144, -v72
	v_cvt_pk_bf16_f32 v73, v145, s0
	v_lshlrev_b32_e32 v144, 1, v132
	v_mov_b32_e32 v145, v1
	v_cvt_pk_bf16_f32 v72, v72, s0
	v_lshl_add_u64 v[62:63], v[62:63], 0, v[144:145]
	global_store_short v[62:63], v72, off offset:128
	global_store_short v[62:63], v73, off offset:160
	global_store_short v[62:63], v72, off offset:320
	global_store_short v[62:63], v73, off offset:352
	global_store_short v[62:63], v72, off offset:512
	global_store_short v[62:63], v73, off offset:544
	global_store_short v[62:63], v72, off offset:704
	global_store_short v[62:63], v73, off offset:736
	v_mul_f32_e32 v72, v43, v147
	v_fma_f32 v72, v59, v146, -v72
	v_mul_f32_e32 v147, v59, v147
	v_cvt_pk_bf16_f32 v72, v72, s0
	v_fmac_f32_e32 v147, v43, v146
	v_cvt_pk_bf16_f32 v146, v147, s0
	global_store_short v[62:63], v72, off offset:130
	global_store_short v[62:63], v146, off offset:162
	global_store_short v[62:63], v72, off offset:322
	global_store_short v[62:63], v146, off offset:354
	global_store_short v[62:63], v72, off offset:514
	global_store_short v[62:63], v146, off offset:546
	global_store_short v[62:63], v72, off offset:706
	global_store_short v[62:63], v146, off offset:738
	v_mul_f32_e32 v72, v44, v149
	v_fma_f32 v72, v60, v148, -v72
	v_mul_f32_e32 v149, v60, v149
	v_cvt_pk_bf16_f32 v72, v72, s0
	v_fmac_f32_e32 v149, v44, v148
	v_cvt_pk_bf16_f32 v148, v149, s0
	global_store_short v[62:63], v72, off offset:132
	global_store_short v[62:63], v148, off offset:164
	global_store_short v[62:63], v72, off offset:324
	global_store_short v[62:63], v148, off offset:356
	global_store_short v[62:63], v72, off offset:516
	global_store_short v[62:63], v148, off offset:548
	global_store_short v[62:63], v72, off offset:708
	global_store_short v[62:63], v148, off offset:740
	v_mul_f32_e32 v70, v45, v151
	v_fma_f32 v70, v61, v150, -v70
	v_mul_f32_e32 v151, v61, v151
	v_cvt_pk_bf16_f32 v70, v70, s0
	v_fmac_f32_e32 v151, v45, v150
	v_cvt_pk_bf16_f32 v150, v151, s0
	global_store_short v[62:63], v70, off offset:134
	global_store_short v[62:63], v150, off offset:166
	global_store_short v[62:63], v70, off offset:326
	global_store_short v[62:63], v150, off offset:358
	global_store_short v[62:63], v70, off offset:518
	global_store_short v[62:63], v150, off offset:550
	global_store_short v[62:63], v70, off offset:710
	global_store_short v[62:63], v150, off offset:742

; DI void phase_inproj(const Prm& p, unsigned char* smem_raw, int l, int S, int& base) {
;     ...
;                 if (nb == 4160) {
;                   const f32x4 v2 = acc[ai][bj][(m + 1) & 3][n];
;                   const int pos = tok & (S - 1);
; #pragma unroll
;                   for (int j = 0; j < 4; ++j) {
;                     const int ii = fq * 4 + j;
;                     const float2 cs = p.rope[pos * 16 + ii];
;                     const u16 o1 = f2bf(v[j] * cs.x - v2[j] * cs.y), o2 = f2bf(v[j] * cs.y + v2[j] * cs.x);
; #pragma unroll
;                     for (int hh = 0; hh < 4; ++hh) {
;                       p.kc[(size_t)tok * 384 + hh * 96 + 64 + ii] = o1;
;                       p.kc[(size_t)tok * 384 + hh * 96 + 80 + ii] = o2;
;                     }
;                   }
;                 }
.LBB0_1428:
	s_andn2_b64 vcc, exec, s[54:55]
	s_cbranch_vccnz .LBB0_1431
	s_andn2_b64 vcc, exec, s[4:5]
	s_cbranch_vccnz .LBB0_1431
	v_readlane_b32 s36, v252, 0
	v_readlane_b32 s8, v254, 45
	v_readlane_b32 s37, v252, 1
	v_readlane_b32 s38, v252, 2
	v_readlane_b32 s39, v252, 3
	v_readlane_b32 s40, v252, 4
	v_readlane_b32 s41, v252, 5
	v_readlane_b32 s42, v252, 6
	v_readlane_b32 s43, v252, 7
	v_and_b32_e32 v60, s8, v122
	v_mov_b64_e32 v[58:59], s[36:37]
	v_readlane_b32 s36, v253, 8
	v_lshl_or_b32 v60, v60, 4, v132
	v_mov_b32_e32 v61, v1
	v_readlane_b32 s40, v253, 12
	v_readlane_b32 s41, v253, 13
	v_mad_i64_i32 v[58:59], s[54:55], v122, s33, v[58:59]
	s_nop 0
	v_lshl_add_u64 v[60:61], v[60:61], 3, s[40:41]
	global_load_dwordx2 v[144:145], v[60:61], off
	global_load_dwordx2 v[146:147], v[60:61], off offset:8
	global_load_dwordx2 v[148:149], v[60:61], off offset:16
	global_load_dwordx2 v[150:151], v[60:61], off offset:24
	v_readlane_b32 s37, v253, 9
	v_readlane_b32 s38, v253, 10
	v_readlane_b32 s39, v253, 11
	v_readlane_b32 s42, v253, 14
	v_readlane_b32 s43, v253, 15
	v_readlane_b32 s44, v253, 16
	v_readlane_b32 s45, v253, 17
	v_readlane_b32 s46, v253, 18
	v_readlane_b32 s47, v253, 19
	v_readlane_b32 s48, v253, 20
	v_readlane_b32 s49, v253, 21
	v_readlane_b32 s50, v253, 22
	v_readlane_b32 s51, v253, 23
	s_waitcnt vmcnt(0)
	v_mul_f32_e32 v64, v38, v145
	v_mul_f32_e32 v145, v54, v145
	v_fmac_f32_e32 v145, v38, v144
	v_fma_f32 v64, v54, v144, -v64
	v_cvt_pk_bf16_f32 v65, v145, s0
	v_lshlrev_b32_e32 v144, 1, v132
	v_mov_b32_e32 v145, v1
	v_cvt_pk_bf16_f32 v64, v64, s0
	v_lshl_add_u64 v[58:59], v[58:59], 0, v[144:145]
	global_store_short v[58:59], v64, off offset:128
	global_store_short v[58:59], v65, off offset:160
	global_store_short v[58:59], v64, off offset:320
	global_store_short v[58:59], v65, off offset:352
	global_store_short v[58:59], v64, off offset:512
	global_store_short v[58:59], v65, off offset:544
	global_store_short v[58:59], v64, off offset:704
	global_store_short v[58:59], v65, off offset:736
	v_mul_f32_e32 v64, v39, v147
	v_fma_f32 v64, v55, v146, -v64
	v_mul_f32_e32 v147, v55, v147
	v_cvt_pk_bf16_f32 v64, v64, s0
	v_fmac_f32_e32 v147, v39, v146
	v_cvt_pk_bf16_f32 v146, v147, s0
	global_store_short v[58:59], v64, off offset:130
	global_store_short v[58:59], v146, off offset:162
	global_store_short v[58:59], v64, off offset:322
	global_store_short v[58:59], v146, off offset:354
	global_store_short v[58:59], v64, off offset:514
	global_store_short v[58:59], v146, off offset:546
	global_store_short v[58:59], v64, off offset:706
	global_store_short v[58:59], v146, off offset:738
	v_mul_f32_e32 v64, v40, v149
	v_fma_f32 v64, v56, v148, -v64
	v_mul_f32_e32 v149, v56, v149
	v_cvt_pk_bf16_f32 v64, v64, s0
	v_fmac_f32_e32 v149, v40, v148
	v_cvt_pk_bf16_f32 v148, v149, s0
	global_store_short v[58:59], v64, off offset:132
	global_store_short v[58:59], v148, off offset:164
	global_store_short v[58:59], v64, off offset:324
	global_store_short v[58:59], v148, off offset:356
	global_store_short v[58:59], v64, off offset:516
	global_store_short v[58:59], v148, off offset:548
	global_store_short v[58:59], v64, off offset:708
	global_store_short v[58:59], v148, off offset:740
	v_mul_f32_e32 v62, v41, v151
	v_fma_f32 v62, v57, v150, -v62
	v_mul_f32_e32 v151, v57, v151
	v_cvt_pk_bf16_f32 v62, v62, s0
	v_fmac_f32_e32 v151, v41, v150
	v_cvt_pk_bf16_f32 v150, v151, s0
	global_store_short v[58:59], v62, off offset:134
	global_store_short v[58:59], v150, off offset:166
	global_store_short v[58:59], v62, off offset:326
	global_store_short v[58:59], v150, off offset:358
	global_store_short v[58:59], v62, off offset:518
	global_store_short v[58:59], v150, off offset:550
	global_store_short v[58:59], v62, off offset:710
	global_store_short v[58:59], v150, off offset:742

; DI void phase_inproj(const Prm& p, unsigned char* smem_raw, int l, int S, int& base) {
;     ...
;                 if (nb == 4160) {
;                   const f32x4 v2 = acc[ai][bj][(m + 1) & 3][n];
;                   const int pos = tok & (S - 1);
; #pragma unroll
;                   for (int j = 0; j < 4; ++j) {
;                     const int ii = fq * 4 + j;
;                     const float2 cs = p.rope[pos * 16 + ii];
;                     const u16 o1 = f2bf(v[j] * cs.x - v2[j] * cs.y), o2 = f2bf(v[j] * cs.y + v2[j] * cs.x);
; #pragma unroll
;                     for (int hh = 0; hh < 4; ++hh) {
;                       p.kc[(size_t)tok * 384 + hh * 96 + 64 + ii] = o1;
;                       p.kc[(size_t)tok * 384 + hh * 96 + 80 + ii] = o2;
;                     }
;                   }
;                 }
.LBB0_1455:
	s_andn2_b64 vcc, exec, s[2:3]
	s_cbranch_vccnz .LBB0_1458
	s_andn2_b64 vcc, exec, s[4:5]
	s_cbranch_vccnz .LBB0_1458
	v_readlane_b32 s36, v252, 0
	v_readlane_b32 s2, v254, 45
	v_readlane_b32 s37, v252, 1
	v_readlane_b32 s38, v252, 2
	v_readlane_b32 s39, v252, 3
	v_readlane_b32 s40, v252, 4
	v_readlane_b32 s41, v252, 5
	v_readlane_b32 s42, v252, 6
	v_readlane_b32 s43, v252, 7
	v_and_b32_e32 v56, s2, v118
	v_mov_b64_e32 v[54:55], s[36:37]
	v_readlane_b32 s36, v253, 8
	v_lshl_or_b32 v56, v56, 4, v132
	v_mov_b32_e32 v57, v1
	v_readlane_b32 s40, v253, 12
	v_readlane_b32 s41, v253, 13
	v_mad_i64_i32 v[54:55], s[2:3], v118, s33, v[54:55]
	s_nop 0
	v_lshl_add_u64 v[56:57], v[56:57], 3, s[40:41]
	global_load_dwordx2 v[144:145], v[56:57], off
	global_load_dwordx2 v[146:147], v[56:57], off offset:8
	global_load_dwordx2 v[148:149], v[56:57], off offset:16
	global_load_dwordx2 v[150:151], v[56:57], off offset:24
	v_readlane_b32 s37, v253, 9
	v_readlane_b32 s38, v253, 10
	v_readlane_b32 s39, v253, 11
	v_readlane_b32 s42, v253, 14
	v_readlane_b32 s43, v253, 15
	v_readlane_b32 s44, v253, 16
	v_readlane_b32 s45, v253, 17
	v_readlane_b32 s46, v253, 18
	v_readlane_b32 s47, v253, 19
	v_readlane_b32 s48, v253, 20
	v_readlane_b32 s49, v253, 21
	v_readlane_b32 s50, v253, 22
	v_readlane_b32 s51, v253, 23
	s_waitcnt vmcnt(0)
	v_mul_f32_e32 v60, v34, v145
	v_mul_f32_e32 v145, v50, v145
	v_fmac_f32_e32 v145, v34, v144
	v_fma_f32 v60, v50, v144, -v60
	v_cvt_pk_bf16_f32 v61, v145, s0
	v_lshlrev_b32_e32 v144, 1, v132
	v_mov_b32_e32 v145, v1
	v_cvt_pk_bf16_f32 v60, v60, s0
	v_lshl_add_u64 v[54:55], v[54:55], 0, v[144:145]
	global_store_short v[54:55], v60, off offset:128
	global_store_short v[54:55], v61, off offset:160
	global_store_short v[54:55], v60, off offset:320
	global_store_short v[54:55], v61, off offset:352
	global_store_short v[54:55], v60, off offset:512
	global_store_short v[54:55], v61, off offset:544
	global_store_short v[54:55], v60, off offset:704
	global_store_short v[54:55], v61, off offset:736
	v_mul_f32_e32 v60, v35, v147
	v_fma_f32 v60, v51, v146, -v60
	v_mul_f32_e32 v147, v51, v147
	v_cvt_pk_bf16_f32 v60, v60, s0
	v_fmac_f32_e32 v147, v35, v146
	v_cvt_pk_bf16_f32 v146, v147, s0
	global_store_short v[54:55], v60, off offset:130
	global_store_short v[54:55], v146, off offset:162
	global_store_short v[54:55], v60, off offset:322
	global_store_short v[54:55], v146, off offset:354
	global_store_short v[54:55], v60, off offset:514
	global_store_short v[54:55], v146, off offset:546
	global_store_short v[54:55], v60, off offset:706
	global_store_short v[54:55], v146, off offset:738
	v_mul_f32_e32 v60, v36, v149
	v_fma_f32 v60, v52, v148, -v60
	v_mul_f32_e32 v149, v52, v149
	v_cvt_pk_bf16_f32 v60, v60, s0
	v_fmac_f32_e32 v149, v36, v148
	v_cvt_pk_bf16_f32 v148, v149, s0
	global_store_short v[54:55], v60, off offset:132
	global_store_short v[54:55], v148, off offset:164
	global_store_short v[54:55], v60, off offset:324
	global_store_short v[54:55], v148, off offset:356
	global_store_short v[54:55], v60, off offset:516
	global_store_short v[54:55], v148, off offset:548
	global_store_short v[54:55], v60, off offset:708
	global_store_short v[54:55], v148, off offset:740
	v_mul_f32_e32 v58, v37, v151
	v_fma_f32 v58, v53, v150, -v58
	v_mul_f32_e32 v151, v53, v151
	v_cvt_pk_bf16_f32 v58, v58, s0
	v_fmac_f32_e32 v151, v37, v150
	v_cvt_pk_bf16_f32 v150, v151, s0
	global_store_short v[54:55], v58, off offset:134
	global_store_short v[54:55], v150, off offset:166
	global_store_short v[54:55], v58, off offset:326
	global_store_short v[54:55], v150, off offset:358
	global_store_short v[54:55], v58, off offset:518
	global_store_short v[54:55], v150, off offset:550
	global_store_short v[54:55], v58, off offset:710
	global_store_short v[54:55], v150, off offset:742

; DI void st4bf(u16* dst, float a, float b, float c, float d) { u32x2 v; v[0] = pack2(a, b); v[1] = pack2(c, d); *(u32x2*)dst = v; }
; DI void phase_norm(const Prm& p, const float* xsrc, const float* g, const float* modl, int shoff, int scoff, int sb) {
;     ...
;   for (int row = gw; row < TB; row += nw) {
;     const int cond = condrow(sb, row);
;     const float* xr = xsrc + (size_t)row * 1024;
;     float4 v[4];
;     float ss = 0.f;
; #pragma unroll
;     for (int i = 0; i < 4; ++i) {
;       v[i] = *(const float4*)(xr + i * 256 + lane * 4);
;       ss += v[i].x * v[i].x + v[i].y * v[i].y + v[i].z * v[i].z + v[i].w * v[i].w;
;     }
; #pragma unroll
;     for (int off = 32; off >= 1; off >>= 1) ss += __shfl_xor(ss, off);
;     const float rstd = rsqrtf(ss * (1.f / 1024.f) + 1e-6f);
;     const float* sc = modl + cond * 6144 + scoff;
;     const float* sh = modl + cond * 6144 + shoff;
; #pragma unroll
;     for (int i = 0; i < 4; ++i) {
;       const int col = i * 256 + lane * 4;
;       const float4 gg = *(const float4*)(g + col), s4 = *(const float4*)(sc + col), h4 = *(const float4*)(sh + col);
;       st4bf(p.hbuf + (size_t)row * 1024 + col,
;             v[i].x * rstd * gg.x * (1.f + s4.x) + h4.x, v[i].y * rstd * gg.y * (1.f + s4.y) + h4.y,
;             v[i].z * rstd * gg.z * (1.f + s4.z) + h4.z, v[i].w * rstd * gg.w * (1.f + s4.w) + h4.w);
;     }
.LBB0_2392:
	v_lshrrev_b32_e32 v2, 11, v26
	v_add_u32_e32 v2, s10, v2
	v_mul_lo_u32 v2, v2, s87
	v_cndmask_b32_e64 v2, v2, 0, s[8:9]
	v_ashrrev_i32_e32 v3, 31, v2
	v_lshl_add_u64 v[2:3], v[2:3], 2, s[12:13]
	s_mov_b64 s[4:5], 0x4000
	v_lshl_add_u64 v[18:19], v[2:3], 0, s[4:5]
	s_mov_b64 s[4:5], 0x3000
	v_lshl_add_u64 v[20:21], v[2:3], 0, s[4:5]
	v_lshl_add_u64 v[2:3], v[18:19], 0, v[0:1]
	v_lshl_add_u64 v[4:5], v[20:21], 0, v[0:1]
	global_load_dwordx4 v[14:17], v[30:31], off
	global_load_dwordx4 v[6:9], v[28:29], off
	global_load_dwordx4 v[10:13], v[2:3], off
	s_nop 0
	global_load_dwordx4 v[2:5], v[4:5], off
	v_mov_b32_e32 v35, v1
	v_mov_b32_e32 v37, v1
	v_mov_b32_e32 v39, v1
	v_lshl_add_u64 v[44:45], v[18:19], 0, v[34:35]
	v_lshl_add_u64 v[40:41], v[20:21], 0, v[34:35]
	v_lshl_add_u64 v[52:53], v[18:19], 0, v[38:39]
	v_lshl_add_u64 v[48:49], v[20:21], 0, v[38:39]
	v_add_u32_e32 v26, s84, v26
	global_load_dwordx4 v[72:75], v[30:31], off offset:1024
	global_load_dwordx4 v[76:79], v[30:31], off offset:2048
	global_load_dwordx4 v[80:83], v[30:31], off offset:3072
	global_load_dwordx4 v[84:87], v[28:29], off offset:1024
	global_load_dwordx4 v[88:91], v[44:45], off
	global_load_dwordx4 v[92:95], v[40:41], off
	global_load_dwordx4 v[96:99], v[28:29], off offset:2048
	v_lshl_add_u64 v[120:121], v[18:19], 0, v[36:37]
	global_load_dwordx4 v[100:103], v[120:121], off
	v_lshl_add_u64 v[122:123], v[20:21], 0, v[36:37]
	global_load_dwordx4 v[104:107], v[122:123], off
	global_load_dwordx4 v[108:111], v[28:29], off offset:3072
	global_load_dwordx4 v[112:115], v[52:53], off
	global_load_dwordx4 v[116:119], v[48:49], off
	s_waitcnt vmcnt(15)
	v_mov_b32_e32 v46, v15
	v_mov_b32_e32 v42, v14
	s_waitcnt vmcnt(13)
	v_pk_add_f32 v[50:51], v[12:13], 1.0 op_sel_hi:[1,0]
	v_pk_add_f32 v[54:55], v[10:11], 1.0 op_sel_hi:[1,0]
	v_mov_b32_e32 v22, v16
	v_mov_b32_e32 v24, v17
	s_waitcnt vmcnt(11)
	v_mov_b32_e32 v47, v73
	v_mov_b32_e32 v43, v72
	v_pk_mul_f32 v[46:47], v[46:47], v[46:47]
	v_mov_b32_e32 v23, v74
	v_pk_fma_f32 v[42:43], v[42:43], v[42:43], v[46:47]
	v_mov_b32_e32 v25, v75
	v_pk_fma_f32 v[22:23], v[22:23], v[22:23], v[42:43]
	v_lshl_add_u64 v[46:47], v[18:19], 0, v[36:37]
	v_pk_fma_f32 v[62:63], v[24:25], v[24:25], v[22:23]
	v_lshl_add_u64 v[42:43], v[20:21], 0, v[36:37]
	v_add_f32_e32 v27, v62, v63
	v_lshl_add_u64 v[30:31], v[30:31], 0, s[6:7]
	s_waitcnt vmcnt(10)
	v_mov_b32_e32 v70, v77
	s_waitcnt vmcnt(9)
	v_mov_b32_e32 v71, v81
	v_mov_b32_e32 v68, v76
	v_mov_b32_e32 v69, v80
	v_pk_mul_f32 v[70:71], v[70:71], v[70:71]
	v_mov_b32_e32 v64, v78
	v_mov_b32_e32 v65, v82
	v_pk_fma_f32 v[68:69], v[68:69], v[68:69], v[70:71]
	v_mov_b32_e32 v66, v79
	v_mov_b32_e32 v67, v83
	v_pk_fma_f32 v[64:65], v[64:65], v[64:65], v[68:69]
	s_nop 0
	v_pk_fma_f32 v[64:65], v[66:67], v[66:67], v[64:65]
	s_nop 0
	v_add_f32_e32 v27, v27, v64
	v_add_f32_e32 v27, v27, v65
	ds_bpermute_b32 v35, v56, v27
	s_waitcnt lgkmcnt(0)
	v_add_f32_e32 v27, v27, v35
	ds_bpermute_b32 v35, v57, v27
	s_waitcnt lgkmcnt(0)
	v_add_f32_e32 v27, v27, v35
	ds_bpermute_b32 v35, v58, v27
	s_waitcnt lgkmcnt(0)
	v_add_f32_e32 v27, v27, v35
	ds_bpermute_b32 v35, v59, v27
	s_waitcnt lgkmcnt(0)
	v_add_f32_e32 v27, v27, v35
	ds_bpermute_b32 v35, v60, v27
	s_waitcnt lgkmcnt(0)
	v_add_f32_e32 v27, v27, v35
	ds_bpermute_b32 v35, v61, v27
	s_waitcnt lgkmcnt(0)
	v_add_f32_e32 v27, v27, v35
	v_fmamk_f32 v27, v27, 0x3a800000, v225
	v_cmp_gt_f32_e32 vcc, s85, v27
	v_mul_f32_e32 v35, 0x4b800000, v27
	s_nop 0
	v_cndmask_b32_e32 v27, v27, v35, vcc
	v_rsq_f32_e32 v27, v27
	s_nop 0
	v_mul_f32_e32 v35, 0x45800000, v27
	v_cndmask_b32_e32 v62, v27, v35, vcc
	v_pk_mul_f32 v[14:15], v[14:15], v[62:63] op_sel_hi:[1,0]
	v_pk_mul_f32 v[72:73], v[72:73], v[62:63] op_sel_hi:[1,0]
	v_pk_mul_f32 v[6:7], v[6:7], v[14:15]
	v_cmp_lt_i32_e32 vcc, s91, v26
	v_pk_fma_f32 v[2:3], v[54:55], v[6:7], v[2:3]
	v_pk_mul_f32 v[6:7], v[16:17], v[62:63] op_sel_hi:[1,0]
	v_cvt_pk_bf16_f32 v2, v2, v3
	v_pk_mul_f32 v[6:7], v[8:9], v[6:7]
	s_or_b64 s[2:3], vcc, s[2:3]
	v_pk_fma_f32 v[4:5], v[50:51], v[6:7], v[4:5]
	s_nop 0
	v_cvt_pk_bf16_f32 v3, v4, v5
	global_store_dwordx2 v[32:33], v[2:3], off offset:-1024
	s_nop 0
	s_waitcnt vmcnt(7)
	v_pk_mul_f32 v[84:85], v[72:73], v[84:85]
	v_pk_add_f32 v[88:89], v[88:89], 1.0 op_sel_hi:[1,0]
	v_pk_fma_f32 v[84:85], v[84:85], v[88:89], v[92:93]
	v_pk_mul_f32 v[88:89], v[74:75], v[62:63] op_sel_hi:[1,0]
	v_cvt_pk_bf16_f32 v84, v84, v85
	v_pk_mul_f32 v[86:87], v[88:89], v[86:87]
	v_pk_add_f32 v[88:89], v[90:91], 1.0 op_sel_hi:[1,0]
	v_pk_mul_f32 v[92:93], v[76:77], v[62:63] op_sel_hi:[1,0]
	v_pk_fma_f32 v[86:87], v[86:87], v[88:89], v[94:95]
	s_nop 0
	v_cvt_pk_bf16_f32 v85, v86, v87
	global_store_dwordx2 v[32:33], v[84:85], off offset:-512
	s_nop 0
	s_waitcnt vmcnt(5)
	v_pk_mul_f32 v[96:97], v[92:93], v[96:97]
	v_pk_add_f32 v[100:101], v[100:101], 1.0 op_sel_hi:[1,0]
	v_pk_mul_f32 v[92:93], v[80:81], v[62:63] op_sel_hi:[1,0]
	v_pk_fma_f32 v[96:97], v[96:97], v[100:101], v[104:105]
	v_pk_mul_f32 v[100:101], v[78:79], v[62:63] op_sel_hi:[1,0]
	v_cvt_pk_bf16_f32 v96, v96, v97
	v_pk_mul_f32 v[98:99], v[100:101], v[98:99]
	v_pk_add_f32 v[100:101], v[102:103], 1.0 op_sel_hi:[1,0]
	s_nop 0
	v_pk_fma_f32 v[98:99], v[98:99], v[100:101], v[106:107]
	s_nop 0
	v_cvt_pk_bf16_f32 v97, v98, v99
	global_store_dwordx2 v[32:33], v[96:97], off
	s_nop 0
	s_waitcnt vmcnt(3)
	v_pk_mul_f32 v[108:109], v[92:93], v[108:109]
	v_pk_add_f32 v[112:113], v[112:113], 1.0 op_sel_hi:[1,0]
	v_pk_fma_f32 v[108:109], v[108:109], v[112:113], v[116:117]
	v_pk_mul_f32 v[112:113], v[82:83], v[62:63] op_sel_hi:[1,0]
	v_cvt_pk_bf16_f32 v108, v108, v109
	v_pk_mul_f32 v[110:111], v[112:113], v[110:111]
	v_pk_add_f32 v[112:113], v[114:115], 1.0 op_sel_hi:[1,0]
	s_nop 0
	v_pk_fma_f32 v[110:111], v[110:111], v[112:113], v[118:119]
	s_nop 0
	v_cvt_pk_bf16_f32 v109, v110, v111
	global_store_dwordx2 v[32:33], v[108:109], off offset:512
	v_lshl_add_u64 v[32:33], v[32:33], 0, s[68:69]
	s_andn2_b64 exec, exec, s[2:3]
	s_cbranch_execnz .LBB0_2392
